# P1 bf16 epilogue: the 16 tile stores per wave are non-temporal (nt), so the next tile's K loop does not wait as long for their acknowledgements
# speedup vs baseline: 1.0275x; 1.0275x over previous
.LBB0_109:
	v_lshl_add_u32 v161, s16, 8, v155
	v_lshl_or_b32 v162, s17, 8, v157
	v_ashrrev_i32_e32 v163, 31, v162
	v_mov_b64_e32 v[164:165], s[74:75]
	v_cvt_pk_bf16_f32 v68, v68, v69
	v_cvt_pk_bf16_f32 v69, v70, v71
	v_cvt_pk_bf16_f32 v70, v64, v65
	v_add_u32_e32 v64, 0x80, v161
	v_mad_i64_i32 v[166:167], s[16:17], v161, s51, v[164:165]
	v_lshlrev_b64 v[162:163], 1, v[162:163]
	v_cvt_pk_bf16_f32 v108, v108, v109
	v_cvt_pk_bf16_f32 v109, v110, v111
	v_cvt_pk_bf16_f32 v110, v104, v105
	v_or_b32_e32 v104, 16, v161
	v_mad_i64_i32 v[64:65], s[16:17], v64, s51, v[164:165]
	v_cvt_pk_bf16_f32 v44, v44, v45
	v_cvt_pk_bf16_f32 v45, v46, v47
	v_cvt_pk_bf16_f32 v46, v40, v41
	v_add_u32_e32 v40, 0x90, v161
	v_lshl_add_u64 v[166:167], v[166:167], 0, v[162:163]
	v_cvt_pk_bf16_f32 v111, v106, v107
	v_mad_i64_i32 v[104:105], s[16:17], v104, s51, v[164:165]
	v_cvt_pk_bf16_f32 v92, v92, v93
	v_cvt_pk_bf16_f32 v93, v94, v95
	v_cvt_pk_bf16_f32 v94, v88, v89
	v_or_b32_e32 v88, 32, v161
	v_lshl_add_u64 v[64:65], v[64:65], 0, v[162:163]
	v_cvt_pk_bf16_f32 v47, v42, v43
	v_mad_i64_i32 v[40:41], s[16:17], v40, s51, v[164:165]
	v_cvt_pk_bf16_f32 v28, v28, v29
	v_cvt_pk_bf16_f32 v29, v30, v31
	v_cvt_pk_bf16_f32 v30, v24, v25
	v_add_u32_e32 v24, 0xa0, v161
	global_store_dwordx4 v[166:167], v[108:111], off offset:256 nt
	v_cvt_pk_bf16_f32 v95, v90, v91
	v_mad_i64_i32 v[88:89], s[16:17], v88, s51, v[164:165]
	v_lshl_add_u64 v[108:109], v[104:105], 0, v[162:163]
	v_cvt_pk_bf16_f32 v76, v76, v77
	v_cvt_pk_bf16_f32 v77, v78, v79
	v_cvt_pk_bf16_f32 v78, v72, v73
	v_or_b32_e32 v72, 48, v161
	global_store_dwordx4 v[64:65], v[44:47], off offset:256 nt
	v_cvt_pk_bf16_f32 v31, v26, v27
	v_mad_i64_i32 v[24:25], s[16:17], v24, s51, v[164:165]
	v_lshl_add_u64 v[44:45], v[40:41], 0, v[162:163]
	v_cvt_pk_bf16_f32 v12, v12, v13
	v_cvt_pk_bf16_f32 v13, v14, v15
	v_cvt_pk_bf16_f32 v14, v8, v9
	v_add_u32_e32 v8, 0xb0, v161
	global_store_dwordx4 v[108:109], v[92:95], off offset:256 nt
	v_cvt_pk_bf16_f32 v79, v74, v75
	v_mad_i64_i32 v[72:73], s[16:17], v72, s51, v[164:165]
	v_lshl_add_u64 v[92:93], v[88:89], 0, v[162:163]
	global_store_dwordx4 v[44:45], v[28:31], off offset:256 nt
	v_cvt_pk_bf16_f32 v15, v10, v11
	v_mad_i64_i32 v[8:9], s[16:17], v8, s51, v[164:165]
	v_lshl_add_u64 v[28:29], v[24:25], 0, v[162:163]
	v_cvt_pk_bf16_f32 v124, v124, v125
	v_cvt_pk_bf16_f32 v125, v126, v127
	v_cvt_pk_bf16_f32 v126, v120, v121
	v_cvt_pk_bf16_f32 v127, v122, v123
	v_cvt_pk_bf16_f32 v104, v116, v117
	v_cvt_pk_bf16_f32 v105, v118, v119
	v_cvt_pk_bf16_f32 v106, v112, v113
	v_cvt_pk_bf16_f32 v107, v114, v115
	v_cvt_pk_bf16_f32 v88, v100, v101
	v_cvt_pk_bf16_f32 v89, v102, v103
	v_cvt_pk_bf16_f32 v90, v96, v97
	v_cvt_pk_bf16_f32 v91, v98, v99
	global_store_dwordx4 v[92:93], v[76:79], off offset:256 nt
	v_cvt_pk_bf16_f32 v74, v80, v81
	v_cvt_pk_bf16_f32 v75, v82, v83
	v_lshl_add_u64 v[76:77], v[72:73], 0, v[162:163]
	v_cvt_pk_bf16_f32 v72, v84, v85
	v_cvt_pk_bf16_f32 v73, v86, v87
	v_cvt_pk_bf16_f32 v71, v66, v67
	v_cvt_pk_bf16_f32 v60, v60, v61
	v_cvt_pk_bf16_f32 v61, v62, v63
	v_cvt_pk_bf16_f32 v62, v56, v57
	v_cvt_pk_bf16_f32 v63, v58, v59
	v_cvt_pk_bf16_f32 v40, v52, v53
	v_cvt_pk_bf16_f32 v41, v54, v55
	v_cvt_pk_bf16_f32 v42, v48, v49
	v_cvt_pk_bf16_f32 v43, v50, v51
	v_cvt_pk_bf16_f32 v24, v36, v37
	v_cvt_pk_bf16_f32 v25, v38, v39
	v_cvt_pk_bf16_f32 v26, v32, v33
	v_cvt_pk_bf16_f32 v27, v34, v35
	global_store_dwordx4 v[28:29], v[12:15], off offset:256 nt
	v_cvt_pk_bf16_f32 v10, v16, v17
	v_cvt_pk_bf16_f32 v11, v18, v19
	v_lshl_add_u64 v[12:13], v[8:9], 0, v[162:163]
	v_cvt_pk_bf16_f32 v8, v20, v21
	v_cvt_pk_bf16_f32 v9, v22, v23
	v_cvt_pk_bf16_f32 v4, v4, v5
	v_cvt_pk_bf16_f32 v5, v6, v7
	v_cvt_pk_bf16_f32 v6, v0, v1
	v_cvt_pk_bf16_f32 v7, v2, v3
	s_andn2_b64 vcc, exec, s[22:23]
	s_mov_b64 s[16:17], -1
	global_store_dwordx4 v[166:167], v[124:127], off nt
	global_store_dwordx4 v[108:109], v[104:107], off nt
	global_store_dwordx4 v[92:93], v[88:91], off nt
	global_store_dwordx4 v[76:77], v[72:75], off nt
	global_store_dwordx4 v[76:77], v[68:71], off offset:256 nt
	global_store_dwordx4 v[64:65], v[60:63], off nt
	global_store_dwordx4 v[44:45], v[40:43], off nt
	global_store_dwordx4 v[28:29], v[24:27], off nt
	global_store_dwordx4 v[12:13], v[8:11], off nt
	global_store_dwordx4 v[12:13], v[4:7], off offset:256 nt
	s_cbranch_vccnz .LBB0_97
	s_andn2_b64 vcc, exec, s[10:11]
	s_cbranch_vccnz .LBB0_96
	s_barrier
	s_branch .LBB0_96
